# norm2 phase: 8 adaLN shift/scale loads issued with the row loads (was 4 dependent rounds with vmcnt(0) each); xor 1,2,4,8 butterfly rounds as DPP adds
# speedup vs baseline: 1.0052x; 1.0021x over previous
; __device__ __forceinline__ void norm_phase(const Args& a, bool from_input, const float* gain, int layer, int shidx) {
;     ...
;     for (int row0 = gw * 4; row0 < MT; row0 += NGW * 4) {
;         f32x4 v[4][4];
;         if (from_input) {
;             const float* xr = row0 < NTP ? a.in[0] + (size_t)row0 * D : a.in[1] + (size_t)(row0 - NTP) * D;
; #pragma unroll
;             for (int rr = 0; rr < 4; ++rr)
; #pragma unroll
;                 for (int j = 0; j < 4; ++j) v[rr][j] = *(const f32x4*)(xr + (size_t)rr * D + 4 * lane + 256 * j);
;         } else {
;             const bf16_t* xr = (const bf16_t*)X + (size_t)row0 * XS;
;             u32x2 t[4][4];
; #pragma unroll
;             for (int rr = 0; rr < 4; ++rr)
; #pragma unroll
;                 for (int j = 0; j < 4; ++j) t[rr][j] = *(const u32x2*)(xr + (size_t)rr * XS + 4 * lane + 256 * j);
; #pragma unroll
;             for (int rr = 0; rr < 4; ++rr)
; #pragma unroll
;                 for (int j = 0; j < 4; ++j) v[rr][j] = (f32x4){__uint_as_float(t[rr][j].x << 16), __uint_as_float(t[rr][j].x & 0xFFFF0000u), __uint_as_float(t[rr][j].y << 16), __uint_as_float(t[rr][j].y & 0xFFFF0000u)};
;         }
;         const float* mp = mod + (size_t)seq_of(row0) * 6144 + shidx * 1024;
;         f32x4 sh[4], sc[4];
; #pragma unroll
;         for (int j = 0; j < 4; ++j) { sh[j] = *(const f32x4*)(mp + 4 * lane + 256 * j); sc[j] = g[j] * (*(const f32x4*)(mp + 1024 + 4 * lane + 256 * j) + 1.f); }
; #pragma unroll
;         for (int rr = 0; rr < 4; ++rr) {
;             float ss = 0.f;
; #pragma unroll
;             for (int j = 0; j < 4; ++j) ss += v[rr][j].x * v[rr][j].x + v[rr][j].y * v[rr][j].y + v[rr][j].z * v[rr][j].z + v[rr][j].w * v[rr][j].w;
; #pragma unroll
;             for (int o = 1; o < 64; o <<= 1) ss += __shfl_xor(ss, o);
.LBB0_2738:
	v_lshl_add_u64 v[18:19], v[40:41], 0, v[36:37]
	v_add_co_u32_e32 v20, vcc, 0x1000, v18
	global_load_dwordx2 v[74:75], v[18:19], off
	global_load_dwordx2 v[76:77], v[18:19], off offset:512
	global_load_dwordx2 v[98:99], v[18:19], off offset:1024
	global_load_dwordx2 v[80:81], v[18:19], off offset:1536
	v_addc_co_u32_e32 v21, vcc, 0, v19, vcc
	global_load_dwordx2 v[94:95], v[20:21], off
	global_load_dwordx2 v[96:97], v[20:21], off offset:512
	global_load_dwordx2 v[90:91], v[20:21], off offset:1024
	global_load_dwordx2 v[92:93], v[20:21], off offset:1536
	v_add_co_u32_e32 v20, vcc, 0x2000, v18
	v_lshl_add_u64 v[108:109], v[38:39], 0, v[36:37]
	s_nop 0
	v_addc_co_u32_e32 v21, vcc, 0, v19, vcc
	v_add_co_u32_e32 v18, vcc, 0x3000, v18
	global_load_dwordx2 v[54:55], v[20:21], off
	global_load_dwordx2 v[56:57], v[20:21], off offset:512
	global_load_dwordx2 v[50:51], v[20:21], off offset:1024
	global_load_dwordx2 v[52:53], v[20:21], off offset:1536
	v_addc_co_u32_e32 v19, vcc, 0, v19, vcc
	global_load_dwordx2 v[46:47], v[18:19], off
	global_load_dwordx2 v[48:49], v[18:19], off offset:512
	global_load_dwordx2 v[42:43], v[18:19], off offset:1024
	global_load_dwordx2 v[44:45], v[18:19], off offset:1536
	v_add_u32_e32 v19, 0xffff0000, v34
	v_lshrrev_b32_e32 v19, 5, v19
	v_cmp_gt_i32_e32 vcc, s14, v34
	v_ashrrev_i32_e32 v18, 11, v34
	v_add_u32_e32 v19, 32, v19
	v_cndmask_b32_e32 v20, v19, v18, vcc
	v_mov_b64_e32 v[18:19], s[4:5]
	v_mad_i64_i32 v[18:19], s[0:1], v20, s9, v[18:19]
	v_lshl_add_u64 v[58:59], v[18:19], 0, v[0:1]
	s_movk_i32 s0, 0x1000
	v_add_co_u32_e32 v18, vcc, s0, v58
	global_load_dwordx4 v[26:29], v[58:59], off
	s_nop 0
	v_addc_co_u32_e32 v19, vcc, 0, v59, vcc
	global_load_dwordx4 v[18:21], v[18:19], off
	v_lshl_add_u64 v[60:61], v[58:59], 0, s[22:23]
	global_load_dwordx4 v[30:33], v[58:59], off offset:1024
	global_load_dwordx4 v[208:211], v[60:61], off offset:1024
	global_load_dwordx4 v[22:25], v[58:59], off offset:2048
	global_load_dwordx4 v[212:215], v[60:61], off offset:2048
	global_load_dwordx4 v[216:219], v[58:59], off offset:3072
	global_load_dwordx4 v[58:61], v[60:61], off offset:3072
	v_add_u32_e32 v34, s8, v34
	v_lshl_add_u64 v[38:39], v[38:39], 0, s[12:13]
	v_lshl_add_u64 v[40:41], v[40:41], 0, s[10:11]
	s_waitcnt vmcnt(23)
	v_and_b32_e32 v84, 0xffff0000, v74
	s_waitcnt vmcnt(22)
	v_and_b32_e32 v85, 0xffff0000, v76
	v_lshlrev_b32_e32 v83, 16, v76
	v_lshlrev_b32_e32 v82, 16, v74
	v_lshlrev_b32_e32 v86, 16, v75
	v_and_b32_e32 v88, 0xffff0000, v75
	v_pk_mul_f32 v[74:75], v[84:85], v[84:85]
	v_lshlrev_b32_e32 v87, 16, v77
	v_pk_fma_f32 v[74:75], v[82:83], v[82:83], v[74:75]
	v_and_b32_e32 v89, 0xffff0000, v77
	v_pk_fma_f32 v[74:75], v[86:87], v[86:87], v[74:75]
	s_waitcnt vmcnt(20)
	v_and_b32_e32 v77, 0xffff0000, v80
	v_and_b32_e32 v76, 0xffff0000, v98
	s_waitcnt vmcnt(18)
	v_and_b32_e32 v103, 0xffff0000, v96
	v_and_b32_e32 v102, 0xffff0000, v94
	v_pk_fma_f32 v[110:111], v[88:89], v[88:89], v[74:75]
	v_lshlrev_b32_e32 v75, 16, v80
	v_lshlrev_b32_e32 v74, 16, v98
	v_and_b32_e32 v80, 0xffff0000, v99
	v_lshlrev_b32_e32 v101, 16, v96
	v_lshlrev_b32_e32 v100, 16, v94
	v_lshlrev_b32_e32 v104, 16, v95
	v_and_b32_e32 v106, 0xffff0000, v95
	v_pk_mul_f32 v[94:95], v[102:103], v[102:103]
	v_lshlrev_b32_e32 v105, 16, v97
	v_pk_fma_f32 v[94:95], v[100:101], v[100:101], v[94:95]
	v_and_b32_e32 v107, 0xffff0000, v97
	v_pk_fma_f32 v[94:95], v[104:105], v[104:105], v[94:95]
	s_waitcnt vmcnt(16)
	v_and_b32_e32 v97, 0xffff0000, v92
	v_and_b32_e32 v96, 0xffff0000, v90
	v_pk_fma_f32 v[120:121], v[106:107], v[106:107], v[94:95]
	v_lshlrev_b32_e32 v95, 16, v92
	v_lshlrev_b32_e32 v94, 16, v90
	v_and_b32_e32 v92, 0xffff0000, v91
	s_waitcnt vmcnt(0)
	v_pk_add_f32 v[20:21], v[20:21], 1.0 op_sel_hi:[1,0]
	v_pk_add_f32 v[18:19], v[18:19], 1.0 op_sel_hi:[1,0]
	v_pk_mul_f32 v[70:71], v[4:5], v[20:21]
	v_pk_mul_f32 v[72:73], v[2:3], v[18:19]
	v_mov_b64_e32 v[18:19], v[216:217]
	v_mov_b64_e32 v[20:21], v[218:219]
	v_mov_b32_e32 v122, v120
	v_mov_b32_e32 v123, v110
	v_mov_b32_e32 v110, v121
	v_pk_add_f32 v[110:111], v[122:123], v[110:111]
	v_mov_b32_e32 v122, v86
	v_mov_b32_e32 v123, v88
	v_mov_b32_e32 v88, v87
	v_lshlrev_b32_e32 v87, 16, v48
	v_lshlrev_b32_e32 v86, 16, v46
	v_pk_add_f32 v[210:211], v[210:211], 1.0 op_sel_hi:[1,0]
	v_pk_add_f32 v[208:209], v[208:209], 1.0 op_sel_hi:[1,0]
	v_pk_mul_f32 v[66:67], v[8:9], v[210:211]
	v_pk_mul_f32 v[68:69], v[6:7], v[208:209]
	v_pk_add_f32 v[214:215], v[214:215], 1.0 op_sel_hi:[1,0]
	v_pk_add_f32 v[212:213], v[212:213], 1.0 op_sel_hi:[1,0]
	v_pk_mul_f32 v[62:63], v[12:13], v[214:215]
	v_pk_mul_f32 v[64:65], v[10:11], v[212:213]
	v_pk_add_f32 v[60:61], v[60:61], 1.0 op_sel_hi:[1,0]
	v_pk_add_f32 v[78:79], v[58:59], 1.0 op_sel_hi:[1,0]
	v_pk_mul_f32 v[58:59], v[16:17], v[60:61]
	v_pk_mul_f32 v[60:61], v[14:15], v[78:79]
	v_lshlrev_b32_e32 v78, 16, v99
	v_pk_mul_f32 v[98:99], v[76:77], v[76:77]
	v_lshlrev_b32_e32 v79, 16, v81
	v_pk_fma_f32 v[98:99], v[74:75], v[74:75], v[98:99]
	v_and_b32_e32 v81, 0xffff0000, v81
	v_pk_fma_f32 v[98:99], v[78:79], v[78:79], v[98:99]
	s_nop 0
	v_pk_fma_f32 v[112:113], v[80:81], v[80:81], v[98:99]
	v_lshlrev_b32_e32 v98, 16, v91
	v_pk_mul_f32 v[90:91], v[96:97], v[96:97]
	v_lshlrev_b32_e32 v99, 16, v93
	v_pk_fma_f32 v[90:91], v[94:95], v[94:95], v[90:91]
	v_and_b32_e32 v93, 0xffff0000, v93
	v_pk_fma_f32 v[90:91], v[98:99], v[98:99], v[90:91]
	v_mov_b32_e32 v121, v112
	v_pk_fma_f32 v[90:91], v[92:93], v[92:93], v[90:91]
	s_nop 0
	v_mov_b32_e32 v120, v90
	v_pk_add_f32 v[110:111], v[110:111], v[120:121]
	v_mov_b32_e32 v112, v91
	v_pk_add_f32 v[90:91], v[110:111], v[112:113]
	v_mov_b32_e32 v120, v82
	v_mov_b32_e32 v121, v84
	v_mov_b32_e32 v84, v83
	s_nop 1
	v_add_f32_dpp v90, v90, v90 quad_perm:[1,0,3,2] row_mask:0xf bank_mask:0xf
	v_add_f32_dpp v91, v91, v91 quad_perm:[1,0,3,2] row_mask:0xf bank_mask:0xf
	s_nop 0
	v_add_f32_dpp v90, v90, v90 quad_perm:[2,3,0,1] row_mask:0xf bank_mask:0xf
	v_add_f32_dpp v91, v91, v91 quad_perm:[2,3,0,1] row_mask:0xf bank_mask:0xf
	s_nop 0
	v_add_f32_dpp v90, v90, v90 row_half_mirror row_mask:0xf bank_mask:0xf
	v_add_f32_dpp v91, v91, v91 row_half_mirror row_mask:0xf bank_mask:0xf
	s_nop 0
	v_add_f32_dpp v90, v90, v90 row_mirror row_mask:0xf bank_mask:0xf
	v_add_f32_dpp v91, v91, v91 row_mirror row_mask:0xf bank_mask:0xf
	ds_bpermute_b32 v111, v118, v91
	ds_bpermute_b32 v110, v118, v90
	s_waitcnt lgkmcnt(0)
; __device__ __forceinline__ unsigned pk2(float lo, float hi) { const f32x2 v = {lo, hi}; const bf16v2_t b = __builtin_convertvector(v, bf16v2_t); return __builtin_bit_cast(unsigned, b); }
; __device__ __forceinline__ void norm_phase(const Args& a, bool from_input, const float* gain, int layer, int shidx) {
;     ...
;             for (int o = 1; o < 64; o <<= 1) ss += __shfl_xor(ss, o);
;             const float rstd = rsqrtf(ss * (1.f / D) + EPS);
; #pragma unroll
;             for (int j = 0; j < 4; ++j) {
;                 const f32x4 y = v[rr][j] * rstd * sc[j] + sh[j];
;                 u32x2 o; o.x = pk2(y.x, y.y); o.y = pk2(y.z, y.w);
;                 *(u32x2*)(H + (size_t)(row0 + rr) * D + 4 * lane + 256 * j) = o;
;             }
	v_pk_add_f32 v[90:91], v[90:91], v[110:111]
	ds_bpermute_b32 v111, v119, v91
	ds_bpermute_b32 v110, v119, v90
	s_waitcnt lgkmcnt(0)
	v_pk_add_f32 v[90:91], v[90:91], v[110:111]
	v_mov_b64_e32 v[110:111], s[26:27]
	v_pk_fma_f32 v[90:91], v[90:91], s[24:25], v[110:111] op_sel_hi:[1,0,0]
	s_nop 0
	v_mul_f32_e32 v35, 0x4b800000, v91
	v_cmp_gt_f32_e64 s[0:1], s15, v91
	v_cmp_gt_f32_e32 vcc, s15, v90
	s_nop 0
	v_cndmask_b32_e64 v35, v91, v35, s[0:1]
	v_rsq_f32_e32 v35, v35
	s_nop 0
	v_mul_f32_e32 v91, 0x45800000, v35
	v_cndmask_b32_e64 v112, v35, v91, s[0:1]
	v_pk_mul_f32 v[120:121], v[112:113], v[120:121] op_sel_hi:[0,1]
	v_pk_mul_f32 v[122:123], v[112:113], v[122:123] op_sel_hi:[0,1]
	v_pk_fma_f32 v[122:123], v[70:71], v[122:123], v[28:29]
	v_pk_fma_f32 v[120:121], v[72:73], v[120:121], v[26:27]
	v_pk_mul_f32 v[82:83], v[112:113], v[84:85] op_sel_hi:[0,1]
	v_pk_mul_f32 v[84:85], v[112:113], v[88:89] op_sel_hi:[0,1]
	v_cvt_pk_bf16_f32 v120, v120, v121
	v_cvt_pk_bf16_f32 v121, v122, v123
	v_add_co_u32_e64 v122, s[0:1], s16, v108
	v_pk_fma_f32 v[84:85], v[66:67], v[84:85], v[32:33]
	v_pk_fma_f32 v[82:83], v[68:69], v[82:83], v[30:31]
	v_mul_f32_e32 v35, 0x4b800000, v90
	v_addc_co_u32_e64 v123, s[0:1], 0, v109, s[0:1]
	v_cvt_pk_bf16_f32 v82, v82, v83
	v_cvt_pk_bf16_f32 v83, v84, v85
	v_cndmask_b32_e32 v35, v90, v35, vcc
	global_store_dwordx2 v[122:123], v[82:83], off offset:512
	v_mov_b32_e32 v83, v76
	v_mov_b32_e32 v85, v80
	v_mov_b32_e32 v76, v75
	v_mov_b32_e32 v80, v79
	v_rsq_f32_e32 v35, v35
	v_mov_b32_e32 v82, v74
	v_pk_mul_f32 v[74:75], v[112:113], v[76:77] op_sel_hi:[0,1]
	v_pk_mul_f32 v[76:77], v[112:113], v[80:81] op_sel_hi:[0,1]
	v_pk_fma_f32 v[76:77], v[58:59], v[76:77], v[20:21]
	v_pk_fma_f32 v[74:75], v[60:61], v[74:75], v[18:19]
	v_mov_b32_e32 v84, v78
	v_cvt_pk_bf16_f32 v74, v74, v75
	v_cvt_pk_bf16_f32 v75, v76, v77
	global_store_dwordx2 v[122:123], v[74:75], off offset:1536
	v_mul_f32_e32 v74, 0x45800000, v35
	v_cndmask_b32_e32 v74, v35, v74, vcc
	v_mov_b32_e32 v76, v100
	v_mov_b32_e32 v77, v102
	v_mov_b32_e32 v78, v104
	v_mov_b32_e32 v79, v106
	v_pk_mul_f32 v[76:77], v[74:75], v[76:77] op_sel_hi:[0,1]
	v_pk_mul_f32 v[78:79], v[74:75], v[78:79] op_sel_hi:[0,1]
	v_pk_fma_f32 v[78:79], v[70:71], v[78:79], v[28:29]
	v_pk_fma_f32 v[76:77], v[72:73], v[76:77], v[26:27]
	v_mov_b32_e32 v102, v101
	v_cvt_pk_bf16_f32 v76, v76, v77
	v_cvt_pk_bf16_f32 v77, v78, v79
	v_mov_b32_e32 v106, v105
	global_store_dwordx2 v[122:123], v[76:77], off offset:2048
	v_pk_mul_f32 v[76:77], v[74:75], v[102:103] op_sel_hi:[0,1]
	v_pk_mul_f32 v[78:79], v[74:75], v[106:107] op_sel_hi:[0,1]
	v_pk_fma_f32 v[78:79], v[66:67], v[78:79], v[32:33]
	v_pk_fma_f32 v[76:77], v[68:69], v[76:77], v[30:31]
	v_pk_mul_f32 v[82:83], v[112:113], v[82:83] op_sel_hi:[0,1]
	v_cvt_pk_bf16_f32 v76, v76, v77
	v_cvt_pk_bf16_f32 v77, v78, v79
	global_store_dwordx2 v[122:123], v[76:77], off offset:2560
	v_mov_b32_e32 v76, v94
	v_mov_b32_e32 v77, v96
	v_mov_b32_e32 v78, v98
	v_mov_b32_e32 v79, v92
	v_pk_mul_f32 v[76:77], v[74:75], v[76:77] op_sel_hi:[0,1]
	v_pk_mul_f32 v[78:79], v[74:75], v[78:79] op_sel_hi:[0,1]
	v_pk_fma_f32 v[78:79], v[62:63], v[78:79], v[24:25]
	v_pk_fma_f32 v[76:77], v[64:65], v[76:77], v[22:23]
	v_mov_b32_e32 v96, v95
	v_cvt_pk_bf16_f32 v76, v76, v77
	v_cvt_pk_bf16_f32 v77, v78, v79
	v_mov_b32_e32 v92, v99
	global_store_dwordx2 v[122:123], v[76:77], off offset:3072
	v_pk_mul_f32 v[76:77], v[74:75], v[96:97] op_sel_hi:[0,1]
	v_pk_mul_f32 v[74:75], v[74:75], v[92:93] op_sel_hi:[0,1]
	v_pk_mul_f32 v[84:85], v[112:113], v[84:85] op_sel_hi:[0,1]
	v_pk_fma_f32 v[74:75], v[58:59], v[74:75], v[20:21]
	v_pk_fma_f32 v[76:77], v[60:61], v[76:77], v[18:19]
	v_pk_fma_f32 v[84:85], v[62:63], v[84:85], v[24:25]
	v_pk_fma_f32 v[82:83], v[64:65], v[82:83], v[22:23]
	v_cvt_pk_bf16_f32 v76, v76, v77
	v_cvt_pk_bf16_f32 v77, v74, v75
	v_cvt_pk_bf16_f32 v82, v82, v83
	v_cvt_pk_bf16_f32 v83, v84, v85
	global_store_dwordx2 v[122:123], v[76:77], off offset:3584
	v_and_b32_e32 v77, 0xffff0000, v56
	v_and_b32_e32 v76, 0xffff0000, v54
	v_and_b32_e32 v89, 0xffff0000, v48
	v_and_b32_e32 v88, 0xffff0000, v46
	global_store_dwordx2 v[122:123], v[82:83], off offset:1024
	v_lshlrev_b32_e32 v75, 16, v56
	v_lshlrev_b32_e32 v74, 16, v54
	v_lshlrev_b32_e32 v78, 16, v55
	v_and_b32_e32 v56, 0xffff0000, v55
	v_pk_mul_f32 v[54:55], v[76:77], v[76:77]
	v_and_b32_e32 v83, 0xffff0000, v52
	v_and_b32_e32 v82, 0xffff0000, v50
	v_lshlrev_b32_e32 v90, 16, v47
	v_and_b32_e32 v48, 0xffff0000, v47
	v_pk_mul_f32 v[46:47], v[88:89], v[88:89]
	v_and_b32_e32 v95, 0xffff0000, v44
	v_and_b32_e32 v94, 0xffff0000, v42
	v_lshlrev_b32_e32 v79, 16, v57
	v_pk_fma_f32 v[54:55], v[74:75], v[74:75], v[54:55]
	v_lshlrev_b32_e32 v81, 16, v52
	v_lshlrev_b32_e32 v80, 16, v50
	v_lshlrev_b32_e32 v84, 16, v51
	v_and_b32_e32 v52, 0xffff0000, v51
	v_pk_mul_f32 v[50:51], v[82:83], v[82:83]
	v_lshlrev_b32_e32 v91, 16, v49
	v_pk_fma_f32 v[46:47], v[86:87], v[86:87], v[46:47]
	v_lshlrev_b32_e32 v93, 16, v44
	v_lshlrev_b32_e32 v92, 16, v42
	v_lshlrev_b32_e32 v96, 16, v43
	v_and_b32_e32 v44, 0xffff0000, v43
	v_pk_mul_f32 v[42:43], v[94:95], v[94:95]
	v_and_b32_e32 v57, 0xffff0000, v57
	v_pk_fma_f32 v[54:55], v[78:79], v[78:79], v[54:55]
	v_lshlrev_b32_e32 v85, 16, v53
	v_pk_fma_f32 v[50:51], v[80:81], v[80:81], v[50:51]
	v_and_b32_e32 v49, 0xffff0000, v49
	v_pk_fma_f32 v[46:47], v[90:91], v[90:91], v[46:47]
	v_lshlrev_b32_e32 v97, 16, v45
	v_pk_fma_f32 v[42:43], v[92:93], v[92:93], v[42:43]
	v_pk_fma_f32 v[54:55], v[56:57], v[56:57], v[54:55]
	v_and_b32_e32 v53, 0xffff0000, v53
; __device__ __forceinline__ unsigned pk2(float lo, float hi) { const f32x2 v = {lo, hi}; const bf16v2_t b = __builtin_convertvector(v, bf16v2_t); return __builtin_bit_cast(unsigned, b); }
; __device__ __forceinline__ void norm_phase(const Args& a, bool from_input, const float* gain, int layer, int shidx) {
;     ...
;         for (int rr = 0; rr < 4; ++rr) {
;             float ss = 0.f;
; #pragma unroll
;             for (int j = 0; j < 4; ++j) ss += v[rr][j].x * v[rr][j].x + v[rr][j].y * v[rr][j].y + v[rr][j].z * v[rr][j].z + v[rr][j].w * v[rr][j].w;
; #pragma unroll
;             for (int o = 1; o < 64; o <<= 1) ss += __shfl_xor(ss, o);
;             const float rstd = rsqrtf(ss * (1.f / D) + EPS);
; #pragma unroll
;             for (int j = 0; j < 4; ++j) {
;                 const f32x4 y = v[rr][j] * rstd * sc[j] + sh[j];
;                 u32x2 o; o.x = pk2(y.x, y.y); o.y = pk2(y.z, y.w);
;                 *(u32x2*)(H + (size_t)(row0 + rr) * D + 4 * lane + 256 * j) = o;
;             }
;         }
;     }
	v_pk_fma_f32 v[50:51], v[84:85], v[84:85], v[50:51]
	v_pk_fma_f32 v[46:47], v[48:49], v[48:49], v[46:47]
	v_and_b32_e32 v45, 0xffff0000, v45
	v_pk_fma_f32 v[42:43], v[96:97], v[96:97], v[42:43]
	v_pk_fma_f32 v[50:51], v[52:53], v[52:53], v[50:51]
	v_pk_fma_f32 v[42:43], v[44:45], v[44:45], v[42:43]
	v_mov_b32_e32 v98, v46
	v_mov_b32_e32 v99, v54
	v_mov_b32_e32 v54, v47
	v_pk_add_f32 v[46:47], v[98:99], v[54:55]
	v_mov_b32_e32 v54, v42
	v_mov_b32_e32 v55, v50
	v_pk_add_f32 v[46:47], v[46:47], v[54:55]
	v_mov_b32_e32 v50, v43
	v_pk_add_f32 v[42:43], v[46:47], v[50:51]
	v_add_co_u32_e64 v108, s[0:1], s17, v108
	v_mov_b32_e32 v50, v74
	s_nop 0
	v_addc_co_u32_e64 v109, s[0:1], 0, v109, s[0:1]
	v_mov_b32_e32 v51, v76
	v_mov_b32_e32 v54, v78
	v_mov_b32_e32 v55, v56
	v_mov_b32_e32 v76, v75
	v_mov_b32_e32 v56, v79
	global_store_dwordx2 v[108:109], v[120:121], off offset:-4096
	s_nop 1
	v_add_f32_dpp v42, v42, v42 quad_perm:[1,0,3,2] row_mask:0xf bank_mask:0xf
	v_add_f32_dpp v43, v43, v43 quad_perm:[1,0,3,2] row_mask:0xf bank_mask:0xf
	s_nop 0
	v_add_f32_dpp v42, v42, v42 quad_perm:[2,3,0,1] row_mask:0xf bank_mask:0xf
	v_add_f32_dpp v43, v43, v43 quad_perm:[2,3,0,1] row_mask:0xf bank_mask:0xf
	s_nop 0
	v_add_f32_dpp v42, v42, v42 row_half_mirror row_mask:0xf bank_mask:0xf
	v_add_f32_dpp v43, v43, v43 row_half_mirror row_mask:0xf bank_mask:0xf
	s_nop 0
	v_add_f32_dpp v42, v42, v42 row_mirror row_mask:0xf bank_mask:0xf
	v_add_f32_dpp v43, v43, v43 row_mirror row_mask:0xf bank_mask:0xf
	ds_bpermute_b32 v47, v118, v43
	ds_bpermute_b32 v46, v118, v42
	s_waitcnt lgkmcnt(0)
	v_pk_add_f32 v[42:43], v[42:43], v[46:47]
	ds_bpermute_b32 v47, v119, v43
	ds_bpermute_b32 v46, v119, v42
	s_waitcnt lgkmcnt(0)
	v_pk_add_f32 v[42:43], v[42:43], v[46:47]
	s_nop 0
	v_pk_fma_f32 v[42:43], v[42:43], s[24:25], v[110:111] op_sel_hi:[1,0,0]
	s_nop 0
	v_mul_f32_e32 v35, 0x4b800000, v43
	v_cmp_gt_f32_e64 s[0:1], s15, v43
	v_cmp_gt_f32_e32 vcc, s15, v42
	s_nop 0
	v_cndmask_b32_e64 v35, v43, v35, s[0:1]
	v_rsq_f32_e32 v35, v35
	s_nop 0
	v_mul_f32_e32 v43, 0x45800000, v35
	v_cndmask_b32_e64 v46, v35, v43, s[0:1]
	v_pk_mul_f32 v[50:51], v[46:47], v[50:51] op_sel_hi:[0,1]
	v_pk_mul_f32 v[54:55], v[46:47], v[54:55] op_sel_hi:[0,1]
	v_pk_fma_f32 v[54:55], v[70:71], v[54:55], v[28:29]
	v_pk_fma_f32 v[50:51], v[72:73], v[50:51], v[26:27]
	v_mul_f32_e32 v35, 0x4b800000, v42
	v_cvt_pk_bf16_f32 v50, v50, v51
	v_cvt_pk_bf16_f32 v51, v54, v55
	global_store_dwordx2 v[108:109], v[50:51], off
	v_pk_mul_f32 v[50:51], v[46:47], v[76:77] op_sel_hi:[0,1]
	v_pk_mul_f32 v[54:55], v[46:47], v[56:57] op_sel_hi:[0,1]
	v_pk_fma_f32 v[54:55], v[66:67], v[54:55], v[32:33]
	v_pk_fma_f32 v[50:51], v[68:69], v[50:51], v[30:31]
	v_cndmask_b32_e32 v35, v42, v35, vcc
	v_cvt_pk_bf16_f32 v50, v50, v51
	v_cvt_pk_bf16_f32 v51, v54, v55
	global_store_dwordx2 v[108:109], v[50:51], off offset:512
	v_mov_b32_e32 v50, v80
	v_mov_b32_e32 v51, v82
	v_mov_b32_e32 v54, v84
	v_mov_b32_e32 v55, v52
	v_pk_mul_f32 v[50:51], v[46:47], v[50:51] op_sel_hi:[0,1]
	v_pk_mul_f32 v[54:55], v[46:47], v[54:55] op_sel_hi:[0,1]
	v_pk_fma_f32 v[54:55], v[62:63], v[54:55], v[24:25]
	v_pk_fma_f32 v[50:51], v[64:65], v[50:51], v[22:23]
	v_rsq_f32_e32 v35, v35
	v_cvt_pk_bf16_f32 v50, v50, v51
	v_cvt_pk_bf16_f32 v51, v54, v55
	v_mov_b32_e32 v82, v81
	v_mov_b32_e32 v52, v85
	global_store_dwordx2 v[108:109], v[50:51], off offset:1024
	v_pk_mul_f32 v[50:51], v[46:47], v[82:83] op_sel_hi:[0,1]
	v_pk_mul_f32 v[46:47], v[46:47], v[52:53] op_sel_hi:[0,1]
	v_pk_fma_f32 v[46:47], v[58:59], v[46:47], v[20:21]
	v_pk_fma_f32 v[50:51], v[60:61], v[50:51], v[18:19]
	v_mul_f32_e32 v42, 0x45800000, v35
	v_cvt_pk_bf16_f32 v50, v50, v51
	v_cvt_pk_bf16_f32 v51, v46, v47
	global_store_dwordx2 v[108:109], v[50:51], off offset:1536
	v_cndmask_b32_e32 v42, v35, v42, vcc
	v_mov_b32_e32 v46, v86
	v_mov_b32_e32 v47, v88
	v_mov_b32_e32 v50, v90
	v_mov_b32_e32 v51, v48
	v_pk_mul_f32 v[46:47], v[42:43], v[46:47] op_sel_hi:[0,1]
	v_pk_mul_f32 v[50:51], v[42:43], v[50:51] op_sel_hi:[0,1]
	v_pk_fma_f32 v[28:29], v[70:71], v[50:51], v[28:29]
	v_pk_fma_f32 v[26:27], v[72:73], v[46:47], v[26:27]
	v_mov_b32_e32 v88, v87
	v_cvt_pk_bf16_f32 v26, v26, v27
	v_cvt_pk_bf16_f32 v27, v28, v29
	v_mov_b32_e32 v48, v91
	global_store_dwordx2 v[108:109], v[26:27], off offset:2048
	v_pk_mul_f32 v[26:27], v[42:43], v[88:89] op_sel_hi:[0,1]
	v_pk_mul_f32 v[28:29], v[42:43], v[48:49] op_sel_hi:[0,1]
	v_pk_fma_f32 v[28:29], v[66:67], v[28:29], v[32:33]
	v_pk_fma_f32 v[26:27], v[68:69], v[26:27], v[30:31]
	v_cmp_lt_i32_e32 vcc, s18, v34
	v_cvt_pk_bf16_f32 v26, v26, v27
	v_cvt_pk_bf16_f32 v27, v28, v29
	global_store_dwordx2 v[108:109], v[26:27], off offset:2560
	v_mov_b32_e32 v26, v92
	v_mov_b32_e32 v27, v94
	v_mov_b32_e32 v28, v96
	v_mov_b32_e32 v29, v44
	v_pk_mul_f32 v[26:27], v[42:43], v[26:27] op_sel_hi:[0,1]
	v_pk_mul_f32 v[28:29], v[42:43], v[28:29] op_sel_hi:[0,1]
	v_pk_fma_f32 v[24:25], v[62:63], v[28:29], v[24:25]
	v_pk_fma_f32 v[22:23], v[64:65], v[26:27], v[22:23]
	v_mov_b32_e32 v94, v93
	v_cvt_pk_bf16_f32 v22, v22, v23
	v_cvt_pk_bf16_f32 v23, v24, v25
	v_mov_b32_e32 v44, v97
	global_store_dwordx2 v[108:109], v[22:23], off offset:3072
	v_pk_mul_f32 v[22:23], v[42:43], v[94:95] op_sel_hi:[0,1]
	v_pk_mul_f32 v[24:25], v[42:43], v[44:45] op_sel_hi:[0,1]
	v_pk_fma_f32 v[20:21], v[58:59], v[24:25], v[20:21]
	v_pk_fma_f32 v[18:19], v[60:61], v[22:23], v[18:19]
	s_or_b64 s[6:7], vcc, s[6:7]
	v_cvt_pk_bf16_f32 v18, v18, v19
	v_cvt_pk_bf16_f32 v19, v20, v21
	global_store_dwordx2 v[108:109], v[18:19], off offset:3584
	s_andn2_b64 exec, exec, s[6:7]
	s_cbranch_execnz .LBB0_2738
